# GQA loop prefetch with double-buffered P registers (no VALU write right behind an MFMA reading the same registers)
# speedup vs baseline: 1.0636x; 1.0039x over previous
; template <int D>
; DI void attn_pass(const bfr* __restrict__ P, int b, int tq_wave, int qcol, int kcol, int vcol, int key0, int nkt, char* smem, f32x16 (&o)[2]) {
;     ...
;     __syncthreads();
;     if (kt + 1 < nkt) {
;       const bfr* Pn = Pb + (size_t)(kt + 1) * 64 * PW;
;       { int c = gt, row = c >> 3, kc = c & 7; kreg[0] = *(const u32x4*)(Pn + (size_t)row * PW + kcol + kc * 8); vreg[0] = *(const u32x4*)(Pn + (size_t)row * PW + vcol + kc * 8); }
;     }
;     f32x16 s[2];
; #pragma unroll
;     for (int t2 = 0; t2 < 2; ++t2) {
; #pragma unroll
;       for (int i = 0; i < 16; ++i) s[t2][i] = 0.f;
; #pragma unroll
;       for (int ks = 0; ks < KS; ++ks) {
;         bf16x8 a = *(const bf16x8*)(sK + (t2 * 32 + r) * KP + ks * 16 + h * 8);
;         s[t2] = MFMA32(a, qf[ks], s[t2]);
;       }
;     }
;     float mx = s[0][0];
; #pragma unroll
;     for (int i = 0; i < 16; ++i) { mx = fmaxf(mx, s[0][i]); mx = fmaxf(mx, s[1][i]); }
;     mx = fmaxf(mx, __shfl_xor(mx, 32));
;     float mnew = fmaxf(mrun, mx);
;     float alpha = __builtin_amdgcn_exp2f(mrun - mnew);
;     mrun = mnew;
;     float ps = 0.f;
; #pragma unroll
;     for (int i = 0; i < 16; ++i) {
;       s[0][i] = __builtin_amdgcn_exp2f(s[0][i] - mnew); ps += s[0][i];
;       s[1][i] = __builtin_amdgcn_exp2f(s[1][i] - mnew); ps += s[1][i];
;     }
;     lsum = lsum * alpha + ps;
; #pragma unroll
;     for (int i = 0; i < 16; ++i) { accO[0][i] *= alpha; accO[1][i] *= alpha; }
; #pragma unroll
;     for (int t2 = 0; t2 < 2; ++t2)
; #pragma unroll
;       for (int j = 0; j < 2; ++j) {
;         unsigned pk[4];
; #pragma unroll
;         for (int e = 0; e < 4; ++e) pk[e] = pack2(s[t2][8 * j + 2 * e], s[t2][8 * j + 2 * e + 1]);
;         u32x4 pku = {pk[0], pk[1], pk[2], pk[3]};
;         bf16x8 pf = __builtin_bit_cast(bf16x8, pku);
; #pragma unroll
;         for (int dt = 0; dt < 2; ++dt) {
;           const int vsw = (((dt * 32 + r) >> 3) & 7) << 3;
;           const bfr* vrow = sV + (dt * 32 + r) * 72;
;           s16x4 lo = *(const s16x4*)(vrow + ((t2 * 32 + 16 * j + 4 * h) ^ vsw));
;           s16x4 hi = *(const s16x4*)(vrow + ((t2 * 32 + 16 * j + 4 * h + 8) ^ vsw));
;           bf16x8 vf = __builtin_shufflevector(lo, hi, 0, 1, 2, 3, 4, 5, 6, 7);
;           accO[dt] = MFMA32(vf, pf, accO[dt]);
;         }
;       }
.LBB0_412:
	s_bitcmp1_b32 s8, 0
	s_cselect_b32 s9, 0x4800, 0
	s_add_i32 s9, s9, 0
	v_add3_u32 v32, s9, v115, v90
	v_add_u32_e32 v121, s9, v114
	v_mov_b32_e32 v120, v113
	s_waitcnt vmcnt(1)
	ds_write_b128 v32, v[84:87]
	v_add3_u32 v32, s9, v117, v118
	v_add3_u32 v33, s9, v118, v117
	v_add_u32_e32 v113, v121, v152
	s_waitcnt vmcnt(0)
	ds_write_b16 v32, v80 offset:9216
	ds_write_b16_d16_hi v33, v80 offset:9360
	ds_write_b16 v32, v81 offset:9504
	ds_write_b16_d16_hi v33, v81 offset:9648
	ds_write_b16 v32, v82 offset:9792
	ds_write_b16_d16_hi v33, v82 offset:9936
	ds_write_b16 v32, v83 offset:10080
	ds_write_b16_d16_hi v33, v83 offset:10224
	s_waitcnt lgkmcnt(0)
	s_barrier
	global_load_dwordx4 v[84:87], v[92:93], off
	global_load_dwordx4 v[80:83], v[94:95], off
	ds_read_b128 v[126:129], v113
	ds_read_b128 v[130:133], v113 offset:32
	ds_read_b128 v[134:137], v113 offset:64
	ds_read_b128 v[138:141], v113 offset:96
	ds_read_b128 v[142:145], v113 offset:4608
	ds_read_b128 v[146:149], v113 offset:4640
	ds_read_b128 v[154:157], v113 offset:4672
	ds_read_b128 v[158:161], v113 offset:4704
	v_mov_b32_e32 v96, v119
	s_waitcnt lgkmcnt(7)
	v_mfma_f32_32x32x16_bf16 v[32:47], v[126:129], v[76:79], 0
	s_add_i32 s8, s8, 1
	s_waitcnt lgkmcnt(6)
	v_mfma_f32_32x32x16_bf16 v[32:47], v[130:133], v[72:75], v[32:47]
	v_lshl_add_u64 v[92:93], v[92:93], 0, s[10:11]
	s_waitcnt lgkmcnt(5)
	v_mfma_f32_32x32x16_bf16 v[32:47], v[134:137], v[68:71], v[32:47]
	v_lshl_add_u64 v[94:95], v[94:95], 0, s[10:11]
	s_waitcnt lgkmcnt(4)
	v_mfma_f32_32x32x16_bf16 v[32:47], v[138:141], v[64:67], v[32:47]
	s_cmp_lg_u32 s8, 35
	s_waitcnt lgkmcnt(3)
	v_mfma_f32_32x32x16_bf16 v[48:63], v[142:145], v[76:79], 0
	s_waitcnt lgkmcnt(2)
	v_mfma_f32_32x32x16_bf16 v[48:63], v[146:149], v[72:75], v[48:63]
	s_waitcnt lgkmcnt(1)
	v_mfma_f32_32x32x16_bf16 v[48:63], v[154:157], v[68:71], v[48:63]
	s_waitcnt lgkmcnt(0)
	v_mfma_f32_32x32x16_bf16 v[48:63], v[158:161], v[64:67], v[48:63]
	v_add_u32_e32 v180, s9, v116
	v_lshl_add_u32 v164, v112, 1, v121
	v_lshl_add_u32 v165, v111, 1, v121
	v_lshl_add_u32 v166, v110, 1, v180
	v_lshl_add_u32 v167, v109, 1, v180
	v_lshl_add_u32 v168, v108, 1, v121
	v_lshl_add_u32 v169, v107, 1, v121
	v_lshl_add_u32 v170, v106, 1, v180
	v_lshl_add_u32 v171, v105, 1, v180
	v_lshl_add_u32 v172, v104, 1, v121
	v_lshl_add_u32 v173, v103, 1, v180
	v_lshl_add_u32 v174, v102, 1, v180
	v_lshl_add_u32 v175, v100, 1, v121
	v_lshl_add_u32 v176, v101, 1, v121
	v_lshl_add_u32 v177, v99, 1, v180
	v_lshl_add_u32 v178, v98, 1, v180
	v_max_f32_e32 v119, v32, v32
	v_max_f32_e32 v113, v48, v48
	v_max_f32_e32 v113, v119, v113
	v_max3_f32 v113, v113, v33, v49
	v_max3_f32 v113, v113, v34, v50
	v_max3_f32 v113, v113, v35, v51
	v_max3_f32 v113, v113, v36, v52
	v_max3_f32 v113, v113, v37, v53
	v_max3_f32 v113, v113, v38, v54
	v_max3_f32 v113, v113, v39, v55
	v_max3_f32 v113, v113, v40, v56
	v_max3_f32 v113, v113, v41, v57
	v_max3_f32 v113, v113, v42, v58
	v_max3_f32 v113, v113, v43, v59
	v_max3_f32 v113, v113, v44, v60
	v_max3_f32 v113, v113, v45, v61
	v_max3_f32 v113, v113, v46, v62
	v_max3_f32 v113, v113, v47, v63
	ds_bpermute_b32 v119, v91, v113
	s_waitcnt lgkmcnt(0)
	ds_read_b64 v[126:127], v164 offset:9216
	ds_read_b64 v[128:129], v165 offset:9216
	ds_read_b64 v[130:131], v166 offset:9216
	ds_read_b64 v[132:133], v167 offset:9216
	ds_read_b64 v[134:135], v168 offset:9216
	ds_read_b64 v[136:137], v169 offset:9216
	ds_read_b64 v[138:139], v170 offset:9216
	ds_read_b64 v[140:141], v171 offset:9216
	v_max3_f32 v119, v96, v113, v119
	v_sub_f32_e32 v32, v32, v119
	v_sub_f32_e32 v38, v38, v119
	v_exp_f32_e32 v32, v32
	v_sub_f32_e32 v48, v48, v119
	v_sub_f32_e32 v36, v36, v119
	v_exp_f32_e32 v124, v38
	v_sub_f32_e32 v38, v54, v119
	v_exp_f32_e32 v48, v48
	v_sub_f32_e32 v33, v33, v119
	v_exp_f32_e32 v122, v36
	v_sub_f32_e32 v36, v52, v119
	v_exp_f32_e32 v52, v38
	v_sub_f32_e32 v38, v39, v119
	v_exp_f32_e32 v33, v33
	v_sub_f32_e32 v49, v49, v119
	v_sub_f32_e32 v37, v37, v119
	v_exp_f32_e32 v125, v38
	v_sub_f32_e32 v38, v55, v119
	v_exp_f32_e32 v49, v49
	v_sub_f32_e32 v34, v34, v119
	v_exp_f32_e32 v123, v37
	v_sub_f32_e32 v37, v53, v119
	v_exp_f32_e32 v53, v38
	v_sub_f32_e32 v38, v40, v119
	v_sub_f32_e32 v40, v42, v119
	v_sub_f32_e32 v42, v44, v119
	v_exp_f32_e32 v34, v34
	v_sub_f32_e32 v50, v50, v119
	v_exp_f32_e32 v54, v38
	v_sub_f32_e32 v38, v56, v119
	v_exp_f32_e32 v56, v40
	v_sub_f32_e32 v40, v58, v119
	v_exp_f32_e32 v58, v42
	v_sub_f32_e32 v42, v60, v119
	s_waitcnt lgkmcnt(4)
; #define MFMA32(a, b, c) __builtin_amdgcn_mfma_f32_32x32x16_bf16((a), (b), (c), 0, 0, 0)
; DI unsigned pack2(float a, float b) { unsigned r; asm volatile("v_cvt_pk_bf16_f32 %0, %1, %2" : "=v"(r) : "v"(a), "v"(b)); return r; }
; template <int D>
; DI void attn_pass(const bfr* __restrict__ P, int b, int tq_wave, int qcol, int kcol, int vcol, int key0, int nkt, char* smem, f32x16 (&o)[2]) {
;     ...
;     for (int i = 0; i < 16; ++i) {
;       s[0][i] = __builtin_amdgcn_exp2f(s[0][i] - mnew); ps += s[0][i];
;       s[1][i] = __builtin_amdgcn_exp2f(s[1][i] - mnew); ps += s[1][i];
;     }
;     lsum = lsum * alpha + ps;
; #pragma unroll
;     for (int i = 0; i < 16; ++i) { accO[0][i] *= alpha; accO[1][i] *= alpha; }
; #pragma unroll
;     for (int t2 = 0; t2 < 2; ++t2)
; #pragma unroll
;       for (int j = 0; j < 2; ++j) {
;         unsigned pk[4];
; #pragma unroll
;         for (int e = 0; e < 4; ++e) pk[e] = pack2(s[t2][8 * j + 2 * e], s[t2][8 * j + 2 * e + 1]);
;         u32x4 pku = {pk[0], pk[1], pk[2], pk[3]};
;         bf16x8 pf = __builtin_bit_cast(bf16x8, pku);
; #pragma unroll
;         for (int dt = 0; dt < 2; ++dt) {
;           const int vsw = (((dt * 32 + r) >> 3) & 7) << 3;
;           const bfr* vrow = sV + (dt * 32 + r) * 72;
;           s16x4 lo = *(const s16x4*)(vrow + ((t2 * 32 + 16 * j + 4 * h) ^ vsw));
;           s16x4 hi = *(const s16x4*)(vrow + ((t2 * 32 + 16 * j + 4 * h + 8) ^ vsw));
;           bf16x8 vf = __builtin_shufflevector(lo, hi, 0, 1, 2, 3, 4, 5, 6, 7);
;           accO[dt] = MFMA32(vf, pf, accO[dt]);
;         }
;       }
	ds_read_b64 v[142:143], v164 offset:9280
	ds_read_b64 v[144:145], v172 offset:9216
	ds_read_b64 v[146:147], v173 offset:9216
	ds_read_b64 v[148:149], v174 offset:9216
	ds_read_b64 v[154:155], v175 offset:9216
	ds_read_b64 v[156:157], v176 offset:9216
	ds_read_b64 v[158:159], v177 offset:9216
	ds_read_b64 v[160:161], v178 offset:9216
	v_add_f32_e32 v60, 0, v32
	v_exp_f32_e32 v50, v50
	v_sub_f32_e32 v35, v35, v119
	v_add_f32_e32 v60, v48, v60
	v_exp_f32_e32 v35, v35
	v_sub_f32_e32 v51, v51, v119
	v_add_f32_e32 v60, v33, v60
	v_exp_f32_e32 v51, v51
	v_add_f32_e32 v60, v49, v60
	v_add_f32_e32 v60, v34, v60
	v_exp_f32_e32 v36, v36
	v_add_f32_e32 v60, v50, v60
	v_add_f32_e32 v60, v35, v60
	v_exp_f32_e32 v37, v37
	v_add_f32_e32 v60, v51, v60
	v_add_f32_e32 v60, v122, v60
	v_add_f32_e32 v60, v36, v60
	v_add_f32_e32 v60, v123, v60
	v_add_f32_e32 v60, v37, v60
	v_add_f32_e32 v60, v124, v60
	v_exp_f32_e32 v38, v38
	v_sub_f32_e32 v39, v41, v119
	v_add_f32_e32 v60, v52, v60
	v_exp_f32_e32 v55, v39
	v_sub_f32_e32 v39, v57, v119
	v_add_f32_e32 v60, v125, v60
	v_exp_f32_e32 v39, v39
	v_add_f32_e32 v60, v53, v60
	v_add_f32_e32 v60, v54, v60
	v_exp_f32_e32 v40, v40
	v_sub_f32_e32 v41, v43, v119
	v_add_f32_e32 v60, v38, v60
	v_exp_f32_e32 v57, v41
	v_sub_f32_e32 v41, v59, v119
	v_add_f32_e32 v60, v55, v60
	v_exp_f32_e32 v41, v41
	v_add_f32_e32 v60, v39, v60
	v_add_f32_e32 v60, v56, v60
	v_exp_f32_e32 v42, v42
	v_sub_f32_e32 v43, v45, v119
	v_add_f32_e32 v60, v40, v60
	v_exp_f32_e32 v59, v43
	v_sub_f32_e32 v43, v61, v119
	v_add_f32_e32 v60, v57, v60
	v_exp_f32_e32 v43, v43
	v_sub_f32_e32 v44, v46, v119
	v_add_f32_e32 v60, v41, v60
	v_exp_f32_e32 v46, v44
	v_sub_f32_e32 v44, v62, v119
	v_add_f32_e32 v60, v58, v60
	v_exp_f32_e32 v44, v44
	v_sub_f32_e32 v45, v47, v119
	v_add_f32_e32 v60, v42, v60
	v_exp_f32_e32 v47, v45
	v_sub_f32_e32 v45, v63, v119
	v_add_f32_e32 v60, v59, v60
	v_exp_f32_e32 v45, v45
	v_add_f32_e32 v60, v43, v60
	v_add_f32_e32 v60, v46, v60
	v_add_f32_e32 v60, v44, v60
	v_add_f32_e32 v60, v47, v60
	v_add_f32_e32 v113, v45, v60
	v_cvt_pk_bf16_f32 v32, v32, v33
	v_cvt_pk_bf16_f32 v33, v34, v35
	v_cvt_pk_bf16_f32 v34, v122, v123
	v_cvt_pk_bf16_f32 v35, v124, v125
	v_sub_f32_e32 v96, v96, v119
	v_exp_f32_e32 v96, v96
	s_nop 1
	v_pk_mul_f32 v[30:31], v[30:31], v[96:97] op_sel_hi:[1,0]
	v_pk_mul_f32 v[28:29], v[28:29], v[96:97] op_sel_hi:[1,0]
	v_pk_mul_f32 v[26:27], v[26:27], v[96:97] op_sel_hi:[1,0]
	v_pk_mul_f32 v[24:25], v[24:25], v[96:97] op_sel_hi:[1,0]
	v_pk_mul_f32 v[22:23], v[22:23], v[96:97] op_sel_hi:[1,0]
	v_pk_mul_f32 v[20:21], v[20:21], v[96:97] op_sel_hi:[1,0]
	v_pk_mul_f32 v[18:19], v[18:19], v[96:97] op_sel_hi:[1,0]
	v_pk_mul_f32 v[16:17], v[16:17], v[96:97] op_sel_hi:[1,0]
	v_pk_mul_f32 v[14:15], v[14:15], v[96:97] op_sel_hi:[1,0]
	v_pk_mul_f32 v[12:13], v[12:13], v[96:97] op_sel_hi:[1,0]
	s_waitcnt lgkmcnt(0)
	v_mfma_f32_32x32x16_bf16 v[16:31], v[126:129], v[32:35], v[16:31]
	v_mul_f32_e64 v10, v10, v96
	v_mul_f32_e64 v11, v11, v96
	v_pk_mul_f32 v[8:9], v[8:9], v[96:97] op_sel_hi:[1,0]
	v_pk_mul_f32 v[6:7], v[6:7], v[96:97] op_sel_hi:[1,0]
	v_pk_mul_f32 v[4:5], v[4:5], v[96:97] op_sel_hi:[1,0]
	v_pk_mul_f32 v[2:3], v[2:3], v[96:97] op_sel_hi:[1,0]
	v_pk_mul_f32 v[0:1], v[0:1], v[96:97] op_sel_hi:[1,0]
	v_fmac_f32_e32 v113, v120, v96
	s_nop 1
	v_mfma_f32_32x32x16_bf16 v[0:15], v[130:133], v[32:35], v[0:15]
	v_cvt_pk_bf16_f32 v164, v54, v55
	v_cvt_pk_bf16_f32 v165, v56, v57
	v_cvt_pk_bf16_f32 v166, v58, v59
	v_cvt_pk_bf16_f32 v167, v46, v47
	s_nop 1
	v_mfma_f32_32x32x16_bf16 v[16:31], v[134:137], v[164:167], v[16:31]
	s_nop 1
	v_mfma_f32_32x32x16_bf16 v[0:15], v[138:141], v[164:167], v[0:15]
	v_cvt_pk_bf16_f32 v32, v48, v49
	v_cvt_pk_bf16_f32 v33, v50, v51
	v_cvt_pk_bf16_f32 v34, v36, v37
	v_cvt_pk_bf16_f32 v35, v52, v53
	s_nop 1
	v_mfma_f32_32x32x16_bf16 v[16:31], v[142:145], v[32:35], v[16:31]
	s_nop 1
	v_mfma_f32_32x32x16_bf16 v[0:15], v[146:149], v[32:35], v[0:15]
	v_cvt_pk_bf16_f32 v164, v38, v39
	v_cvt_pk_bf16_f32 v165, v40, v41
	v_cvt_pk_bf16_f32 v166, v42, v43
	v_cvt_pk_bf16_f32 v167, v44, v45
	s_nop 1
	v_mfma_f32_32x32x16_bf16 v[16:31], v[154:157], v[164:167], v[16:31]
	s_nop 1
	v_mfma_f32_32x32x16_bf16 v[0:15], v[158:161], v[164:167], v[0:15]
	s_cbranch_scc1 .LBB0_412
	v_add3_u32 v32, 0, v115, v90
	s_waitcnt vmcnt(1)
	ds_write_b128 v32, v[84:87] offset:18432
	v_add3_u32 v32, 0, v117, v118
	v_add3_u32 v33, 0, v118, v117
	s_waitcnt vmcnt(0)
	ds_write_b16 v32, v80 offset:27648
	ds_write_b16_d16_hi v33, v80 offset:27792
	ds_write_b16 v32, v81 offset:27936
	ds_write_b16_d16_hi v33, v81 offset:28080
	ds_write_b16 v32, v82 offset:28224
	ds_write_b16_d16_hi v33, v82 offset:28368
	ds_write_b16 v32, v83 offset:28512
	ds_write_b16_d16_hi v33, v83 offset:28656
	v_add_u32_e32 v80, 0, v114
	v_add_u32_e32 v81, v80, v152
	s_waitcnt lgkmcnt(0)
	s_barrier
; #define MFMA32(a, b, c) __builtin_amdgcn_mfma_f32_32x32x16_bf16((a), (b), (c), 0, 0, 0)
; DI unsigned pack2(float a, float b) { unsigned r; asm volatile("v_cvt_pk_bf16_f32 %0, %1, %2" : "=v"(r) : "v"(a), "v"(b)); return r; }
; template <int D>
; DI void attn_pass(const bfr* __restrict__ P, int b, int tq_wave, int qcol, int kcol, int vcol, int key0, int nkt, char* smem, f32x16 (&o)[2]) {
;     ...
;     f32x16 s[2];
; #pragma unroll
;     for (int t2 = 0; t2 < 2; ++t2) {
; #pragma unroll
;       for (int i = 0; i < 16; ++i) s[t2][i] = 0.f;
; #pragma unroll
;       for (int ks = 0; ks < KS; ++ks) {
;         bf16x8 a = *(const bf16x8*)(sK + (t2 * 32 + r) * KP + ks * 16 + h * 8);
;         s[t2] = MFMA32(a, qf[ks], s[t2]);
;       }
;     }
;     float mx = s[0][0];
; #pragma unroll
;     for (int i = 0; i < 16; ++i) { mx = fmaxf(mx, s[0][i]); mx = fmaxf(mx, s[1][i]); }
;     mx = fmaxf(mx, __shfl_xor(mx, 32));
;     float mnew = fmaxf(mrun, mx);
;     float alpha = __builtin_amdgcn_exp2f(mrun - mnew);
;     mrun = mnew;
;     float ps = 0.f;
; #pragma unroll
;     for (int i = 0; i < 16; ++i) {
;       s[0][i] = __builtin_amdgcn_exp2f(s[0][i] - mnew); ps += s[0][i];
;       s[1][i] = __builtin_amdgcn_exp2f(s[1][i] - mnew); ps += s[1][i];
;     }
;     lsum = lsum * alpha + ps;
; #pragma unroll
;     for (int i = 0; i < 16; ++i) { accO[0][i] *= alpha; accO[1][i] *= alpha; }
; #pragma unroll
;     for (int t2 = 0; t2 < 2; ++t2)
; #pragma unroll
;       for (int j = 0; j < 2; ++j) {
;         unsigned pk[4];
; #pragma unroll
;         for (int e = 0; e < 4; ++e) pk[e] = pack2(s[t2][8 * j + 2 * e], s[t2][8 * j + 2 * e + 1]);
;         u32x4 pku = {pk[0], pk[1], pk[2], pk[3]};
;         bf16x8 pf = __builtin_bit_cast(bf16x8, pku);
; #pragma unroll
;         for (int dt = 0; dt < 2; ++dt) {
;           const int vsw = (((dt * 32 + r) >> 3) & 7) << 3;
;           const bfr* vrow = sV + (dt * 32 + r) * 72;
;           s16x4 lo = *(const s16x4*)(vrow + ((t2 * 32 + 16 * j + 4 * h) ^ vsw));
;           s16x4 hi = *(const s16x4*)(vrow + ((t2 * 32 + 16 * j + 4 * h + 8) ^ vsw));
;           bf16x8 vf = __builtin_shufflevector(lo, hi, 0, 1, 2, 3, 4, 5, 6, 7);
;           accO[dt] = MFMA32(vf, pf, accO[dt]);
;         }
;       }
	ds_read_b128 v[32:35], v81 offset:18432
	ds_read_b128 v[48:51], v81 offset:18464
	s_waitcnt lgkmcnt(1)
	v_mfma_f32_32x32x16_bf16 v[32:47], v[32:35], v[76:79], 0
	v_lshlrev_b32_e32 v152, 1, v88
	s_waitcnt lgkmcnt(0)
	v_mfma_f32_32x32x16_bf16 v[32:47], v[48:51], v[72:75], v[32:47]
	ds_read_b128 v[48:51], v81 offset:18496
	s_waitcnt lgkmcnt(0)
	v_mfma_f32_32x32x16_bf16 v[32:47], v[48:51], v[68:71], v[32:47]
	ds_read_b128 v[48:51], v81 offset:18528
	s_waitcnt lgkmcnt(0)
	v_mfma_f32_32x32x16_bf16 v[32:47], v[48:51], v[64:67], v[32:47]
	ds_read_b128 v[48:51], v81 offset:23040
	s_waitcnt lgkmcnt(0)
	v_mfma_f32_32x32x16_bf16 v[48:63], v[48:51], v[76:79], 0
	ds_read_b128 v[76:79], v81 offset:23072
	s_waitcnt lgkmcnt(0)
	v_mfma_f32_32x32x16_bf16 v[48:63], v[76:79], v[72:75], v[48:63]
	ds_read_b128 v[72:75], v81 offset:23104
	s_waitcnt lgkmcnt(0)
	v_mfma_f32_32x32x16_bf16 v[48:63], v[72:75], v[68:71], v[48:63]
	ds_read_b128 v[68:71], v81 offset:23136
	s_waitcnt lgkmcnt(0)
	v_mfma_f32_32x32x16_bf16 v[48:63], v[68:71], v[64:67], v[48:63]
	v_max_f32_e32 v65, v32, v32
	v_lshl_add_u32 v66, v112, 1, v80
	v_add_u32_e32 v67, 0x1200, v80
	s_nop 8
	v_max_f32_e32 v64, v48, v48
	v_max_f32_e32 v64, v65, v64
	v_max3_f32 v64, v64, v33, v49
	v_max3_f32 v64, v64, v34, v50
	v_max3_f32 v64, v64, v35, v51
	v_max3_f32 v64, v64, v36, v52
	v_max3_f32 v64, v64, v37, v53
	v_max3_f32 v64, v64, v38, v54
	v_max3_f32 v64, v64, v39, v55
	v_max3_f32 v64, v64, v40, v56
	v_max3_f32 v64, v64, v41, v57
	v_max3_f32 v64, v64, v42, v58
	v_max3_f32 v64, v64, v43, v59
	v_max3_f32 v64, v64, v44, v60
	v_max3_f32 v64, v64, v45, v61
	v_max3_f32 v64, v64, v46, v62
	v_max3_f32 v64, v64, v47, v63
	ds_bpermute_b32 v65, v91, v64
	s_waitcnt lgkmcnt(0)
	v_max3_f32 v65, v119, v64, v65
	v_sub_f32_e32 v64, v119, v65
	v_sub_f32_e32 v32, v32, v65
	v_exp_f32_e32 v64, v64
	v_exp_f32_e32 v32, v32
	v_sub_f32_e32 v48, v48, v65
	v_exp_f32_e32 v48, v48
	v_sub_f32_e32 v33, v33, v65
	v_exp_f32_e32 v33, v33
	v_sub_f32_e32 v49, v49, v65
	v_exp_f32_e32 v49, v49
	v_sub_f32_e32 v34, v34, v65
	v_exp_f32_e32 v34, v34
	v_sub_f32_e32 v50, v50, v65
	v_sub_f32_e32 v35, v35, v65
	v_sub_f32_e32 v51, v51, v65
	v_sub_f32_e32 v36, v36, v65
	v_sub_f32_e32 v52, v52, v65
	v_sub_f32_e32 v37, v37, v65
	v_sub_f32_e32 v53, v53, v65
	v_sub_f32_e32 v38, v38, v65
	v_sub_f32_e32 v54, v54, v65
	v_sub_f32_e32 v39, v39, v65
	v_sub_f32_e32 v55, v55, v65
	v_sub_f32_e32 v40, v40, v65
	v_sub_f32_e32 v56, v56, v65
	v_sub_f32_e32 v41, v41, v65
	v_sub_f32_e32 v57, v57, v65
	v_sub_f32_e32 v42, v42, v65
	v_sub_f32_e32 v58, v58, v65
	v_sub_f32_e32 v43, v43, v65
	v_sub_f32_e32 v59, v59, v65
	v_sub_f32_e32 v44, v44, v65
	v_sub_f32_e32 v60, v60, v65
	v_sub_f32_e32 v45, v45, v65
	v_sub_f32_e32 v61, v61, v65
	v_sub_f32_e32 v46, v46, v65
	v_sub_f32_e32 v62, v62, v65
	v_sub_f32_e32 v47, v47, v65
	v_sub_f32_e32 v63, v63, v65
	v_pk_mul_f32 v[30:31], v[30:31], v[64:65] op_sel_hi:[1,0]
	v_pk_mul_f32 v[28:29], v[28:29], v[64:65] op_sel_hi:[1,0]
	v_pk_mul_f32 v[26:27], v[26:27], v[64:65] op_sel_hi:[1,0]
	v_pk_mul_f32 v[24:25], v[24:25], v[64:65] op_sel_hi:[1,0]
	v_pk_mul_f32 v[22:23], v[22:23], v[64:65] op_sel_hi:[1,0]
	v_pk_mul_f32 v[20:21], v[20:21], v[64:65] op_sel_hi:[1,0]
	v_pk_mul_f32 v[18:19], v[18:19], v[64:65] op_sel_hi:[1,0]
	v_pk_mul_f32 v[16:17], v[16:17], v[64:65] op_sel_hi:[1,0]
	v_pk_mul_f32 v[14:15], v[14:15], v[64:65] op_sel_hi:[1,0]
	v_pk_mul_f32 v[12:13], v[12:13], v[64:65] op_sel_hi:[1,0]
	v_pk_mul_f32 v[10:11], v[10:11], v[64:65] op_sel_hi:[1,0]
	v_pk_mul_f32 v[8:9], v[8:9], v[64:65] op_sel_hi:[1,0]
	v_pk_mul_f32 v[6:7], v[6:7], v[64:65] op_sel_hi:[1,0]
	v_pk_mul_f32 v[4:5], v[4:5], v[64:65] op_sel_hi:[1,0]
	v_pk_mul_f32 v[2:3], v[2:3], v[64:65] op_sel_hi:[1,0]
	v_pk_mul_f32 v[0:1], v[0:1], v[64:65] op_sel_hi:[1,0]
	v_add_f32_e32 v65, 0, v32
	v_exp_f32_e32 v50, v50
	v_add_f32_e32 v65, v48, v65
	v_exp_f32_e32 v35, v35
	v_add_f32_e32 v65, v33, v65
	v_exp_f32_e32 v51, v51
	v_add_f32_e32 v65, v49, v65
	v_exp_f32_e32 v36, v36
	v_add_f32_e32 v65, v34, v65
	v_exp_f32_e32 v52, v52
	v_add_f32_e32 v65, v50, v65
	v_exp_f32_e32 v37, v37
	v_add_f32_e32 v65, v35, v65
	v_exp_f32_e32 v53, v53
	v_add_f32_e32 v65, v51, v65
	v_exp_f32_e32 v38, v38
	v_add_f32_e32 v65, v36, v65
	v_exp_f32_e32 v54, v54
	v_add_f32_e32 v65, v52, v65
	v_exp_f32_e32 v39, v39
	v_add_f32_e32 v65, v37, v65
	v_add_f32_e32 v65, v53, v65
	v_add_f32_e32 v65, v38, v65
	v_add_f32_e32 v65, v54, v65
	v_cvt_pk_bf16_f32 v32, v32, v33
	v_cvt_pk_bf16_f32 v33, v34, v35
	v_cvt_pk_bf16_f32 v34, v36, v37
	v_cvt_pk_bf16_f32 v35, v38, v39
	v_lshl_add_u32 v38, v111, 1, v80
	v_add_f32_e32 v65, v39, v65
	ds_read_b64 v[36:37], v66 offset:27648
	ds_read_b64 v[38:39], v38 offset:27648
	s_waitcnt lgkmcnt(0)
	v_mfma_f32_32x32x16_bf16 v[16:31], v[36:39], v[32:35], v[16:31]
	v_lshl_add_u32 v36, v110, 1, v67
	v_lshl_add_u32 v38, v109, 1, v67
	ds_read_b64 v[36:37], v36 offset:27648
	ds_read_b64 v[38:39], v38 offset:27648
	v_exp_f32_e32 v40, v40
	v_exp_f32_e32 v41, v41
	v_exp_f32_e32 v42, v42
	s_waitcnt lgkmcnt(0)
; #define MFMA32(a, b, c) __builtin_amdgcn_mfma_f32_32x32x16_bf16((a), (b), (c), 0, 0, 0)
; DI unsigned pack2(float a, float b) { unsigned r; asm volatile("v_cvt_pk_bf16_f32 %0, %1, %2" : "=v"(r) : "v"(a), "v"(b)); return r; }
; template <int D>
; DI void attn_pass(const bfr* __restrict__ P, int b, int tq_wave, int qcol, int kcol, int vcol, int key0, int nkt, char* smem, f32x16 (&o)[2]) {
;     ...
;     for (int i = 0; i < 16; ++i) { accO[0][i] *= alpha; accO[1][i] *= alpha; }
; #pragma unroll
;     for (int t2 = 0; t2 < 2; ++t2)
; #pragma unroll
;       for (int j = 0; j < 2; ++j) {
;         unsigned pk[4];
; #pragma unroll
;         for (int e = 0; e < 4; ++e) pk[e] = pack2(s[t2][8 * j + 2 * e], s[t2][8 * j + 2 * e + 1]);
;         u32x4 pku = {pk[0], pk[1], pk[2], pk[3]};
;         bf16x8 pf = __builtin_bit_cast(bf16x8, pku);
; #pragma unroll
;         for (int dt = 0; dt < 2; ++dt) {
;           const int vsw = (((dt * 32 + r) >> 3) & 7) << 3;
;           const bfr* vrow = sV + (dt * 32 + r) * 72;
;           s16x4 lo = *(const s16x4*)(vrow + ((t2 * 32 + 16 * j + 4 * h) ^ vsw));
;           s16x4 hi = *(const s16x4*)(vrow + ((t2 * 32 + 16 * j + 4 * h + 8) ^ vsw));
;           bf16x8 vf = __builtin_shufflevector(lo, hi, 0, 1, 2, 3, 4, 5, 6, 7);
;           accO[dt] = MFMA32(vf, pf, accO[dt]);
;         }
;       }
;   }
;   lsum += __shfl_xor(lsum, 32);
;   float inv = 1.f / lsum;
; #pragma unroll
;   for (int i = 0; i < 16; ++i) { o[0][i] = accO[0][i] * inv; o[1][i] = accO[1][i] * inv; }
; DI void store_o(bfr* O, int m, int colbase, int h, const f32x16 (&o)[2]) {
; #pragma unroll
;   for (int dt = 0; dt < 2; ++dt)
; #pragma unroll
;     for (int g4 = 0; g4 < 4; ++g4) {
;       int dv = dt * 32 + 8 * g4 + 4 * h;
;       uint2 pk; pk.x = pack2(o[dt][4 * g4], o[dt][4 * g4 + 1]); pk.y = pack2(o[dt][4 * g4 + 2], o[dt][4 * g4 + 3]);
;       *(uint2*)(O + (size_t)m * DM + colbase + dv) = pk;
;     }
	v_mfma_f32_32x32x16_bf16 v[0:15], v[36:39], v[32:35], v[0:15]
	v_lshl_add_u32 v36, v108, 1, v80
	v_lshl_add_u32 v38, v107, 1, v80
	v_exp_f32_e32 v43, v43
	v_exp_f32_e32 v44, v44
	v_exp_f32_e32 v45, v45
	v_exp_f32_e32 v46, v46
	v_exp_f32_e32 v47, v47
	v_cvt_pk_bf16_f32 v32, v40, v41
	v_cvt_pk_bf16_f32 v33, v42, v43
	v_cvt_pk_bf16_f32 v34, v44, v45
	v_cvt_pk_bf16_f32 v35, v46, v47
	ds_read_b64 v[36:37], v36 offset:27648
	ds_read_b64 v[38:39], v38 offset:27648
	s_waitcnt lgkmcnt(0)
	v_mfma_f32_32x32x16_bf16 v[16:31], v[36:39], v[32:35], v[16:31]
	v_lshl_add_u32 v36, v106, 1, v67
	v_lshl_add_u32 v38, v105, 1, v67
	ds_read_b64 v[36:37], v36 offset:27648
	ds_read_b64 v[38:39], v38 offset:27648
	v_exp_f32_e32 v55, v55
	v_exp_f32_e32 v56, v56
	v_exp_f32_e32 v57, v57
	s_waitcnt lgkmcnt(0)
	v_mfma_f32_32x32x16_bf16 v[0:15], v[36:39], v[32:35], v[0:15]
	v_lshl_add_u32 v38, v104, 1, v80
	v_cvt_pk_bf16_f32 v32, v48, v49
	v_cvt_pk_bf16_f32 v33, v50, v51
	v_cvt_pk_bf16_f32 v34, v52, v53
	v_cvt_pk_bf16_f32 v35, v54, v55
	ds_read_b64 v[36:37], v66 offset:27712
	ds_read_b64 v[38:39], v38 offset:27648
	s_waitcnt lgkmcnt(0)
	v_mfma_f32_32x32x16_bf16 v[16:31], v[36:39], v[32:35], v[16:31]
	v_lshl_add_u32 v36, v103, 1, v67
	v_lshl_add_u32 v38, v102, 1, v67
	ds_read_b64 v[36:37], v36 offset:27648
	ds_read_b64 v[38:39], v38 offset:27648
	v_exp_f32_e32 v58, v58
	v_exp_f32_e32 v59, v59
	v_exp_f32_e32 v60, v60
	s_waitcnt lgkmcnt(0)
	v_mfma_f32_32x32x16_bf16 v[0:15], v[36:39], v[32:35], v[0:15]
	v_lshl_add_u32 v36, v100, 1, v80
	v_lshl_add_u32 v38, v101, 1, v80
	v_exp_f32_e32 v61, v61
	v_exp_f32_e32 v62, v62
	v_exp_f32_e32 v63, v63
	v_cvt_pk_bf16_f32 v32, v56, v57
	v_cvt_pk_bf16_f32 v33, v58, v59
	v_cvt_pk_bf16_f32 v34, v60, v61
	v_cvt_pk_bf16_f32 v35, v62, v63
	ds_read_b64 v[36:37], v36 offset:27648
	ds_read_b64 v[38:39], v38 offset:27648
	v_add_f32_e32 v65, v55, v65
	v_add_f32_e32 v65, v40, v65
	v_add_f32_e32 v65, v56, v65
	v_add_f32_e32 v65, v41, v65
	v_add_f32_e32 v65, v57, v65
	v_add_f32_e32 v65, v42, v65
	v_add_f32_e32 v65, v58, v65
	v_add_f32_e32 v65, v43, v65
	v_add_f32_e32 v65, v59, v65
	s_waitcnt lgkmcnt(0)
	v_mfma_f32_32x32x16_bf16 v[16:31], v[36:39], v[32:35], v[16:31]
	v_lshl_add_u32 v36, v99, 1, v67
	v_lshl_add_u32 v38, v98, 1, v67
	v_add_f32_e32 v65, v44, v65
	ds_read_b64 v[36:37], v36 offset:27648
	ds_read_b64 v[38:39], v38 offset:27648
	v_add_f32_e32 v65, v60, v65
	v_add_f32_e32 v65, v45, v65
	v_add_f32_e32 v65, v61, v65
	v_add_f32_e32 v65, v46, v65
	v_add_f32_e32 v65, v62, v65
	v_add_f32_e32 v65, v47, v65
	v_add_f32_e32 v65, v63, v65
	v_fmac_f32_e32 v65, v113, v64
	s_waitcnt lgkmcnt(0)
	v_mfma_f32_32x32x16_bf16 v[0:15], v[36:39], v[32:35], v[0:15]
	ds_bpermute_b32 v32, v91, v65
	s_waitcnt lgkmcnt(0)
	v_add_f32_e32 v32, v65, v32
	v_div_scale_f32 v33, s[8:9], v32, v32, 1.0
	v_rcp_f32_e32 v34, v33
	s_load_dwordx4 s[8:11], s[0:1], 0x100
	s_waitcnt lgkmcnt(0)
	s_mov_b64 s[8:9], 0x2b7c700
	v_fma_f32 v35, -v33, v34, 1.0
	v_fmac_f32_e32 v34, v35, v34
	v_div_scale_f32 v35, vcc, 1.0, v32, 1.0
	v_mul_f32_e32 v36, v35, v34
	v_fma_f32 v37, -v33, v36, v35
	v_fmac_f32_e32 v36, v37, v34
	v_fma_f32 v33, -v33, v36, v35
	v_div_fmas_f32 v33, v33, v34, v36
	v_div_fixup_f32 v32, v33, v32, 1.0
	v_mul_f32_e32 v33, v0, v32
	v_and_or_b32 v0, v89, 31, v97
	v_mul_f32_e32 v34, v1, v32
	v_ashrrev_i32_e32 v1, 31, v0
	v_lshlrev_b64 v[0:1], 11, v[0:1]
	v_mul_f32_e32 v37, v4, v32
	v_lshl_add_u64 v[0:1], s[10:11], 0, v[0:1]
	v_lshrrev_b32_e32 v4, 2, v89
	v_lshl_add_u64 v[0:1], v[0:1], 0, v[152:153]
	v_and_b32_e32 v152, 8, v4
	v_lshl_add_u64 v[0:1], v[0:1], 0, v[152:153]
	v_mul_f32_e32 v38, v5, v32
	v_lshl_add_u64 v[4:5], v[0:1], 0, s[8:9]
	s_mov_b32 s8, 0x2b7c000
	v_add_co_u32_e32 v0, vcc, s8, v0
	v_mul_f32_e32 v16, v16, v32
	s_nop 0
	v_addc_co_u32_e32 v1, vcc, 0, v1, vcc
	v_mul_f32_e32 v17, v17, v32
	v_mul_f32_e32 v18, v18, v32
	v_mul_f32_e32 v35, v2, v32
	v_mul_f32_e32 v19, v19, v32
	v_mul_f32_e32 v36, v3, v32
	v_mul_f32_e32 v20, v20, v32
	v_mul_f32_e32 v21, v21, v32
	v_mul_f32_e32 v22, v22, v32
	v_mul_f32_e32 v23, v23, v32
	v_cvt_pk_bf16_f32 v2, v16, v17
	v_cvt_pk_bf16_f32 v3, v18, v19
	global_store_dwordx2 v[0:1], v[2:3], off offset:1792
	v_cvt_pk_bf16_f32 v0, v20, v21
	v_cvt_pk_bf16_f32 v1, v22, v23
	v_mul_f32_e32 v24, v24, v32
	v_mul_f32_e32 v25, v25, v32
	v_mul_f32_e32 v26, v26, v32
	v_mul_f32_e32 v27, v27, v32
	global_store_dwordx2 v[4:5], v[0:1], off offset:16
	v_cvt_pk_bf16_f32 v0, v24, v25
	v_cvt_pk_bf16_f32 v1, v26, v27
	v_mul_f32_e32 v28, v28, v32
	v_mul_f32_e32 v29, v29, v32
	v_mul_f32_e32 v30, v30, v32
	v_mul_f32_e32 v31, v31, v32
	global_store_dwordx2 v[4:5], v[0:1], off offset:32
	v_cvt_pk_bf16_f32 v0, v28, v29
	v_cvt_pk_bf16_f32 v1, v30, v31
	global_store_dwordx2 v[4:5], v[0:1], off offset:48
	v_cvt_pk_bf16_f32 v0, v33, v34
	v_cvt_pk_bf16_f32 v1, v35, v36
	v_mul_f32_e32 v6, v6, v32
	v_mul_f32_e32 v7, v7, v32
	global_store_dwordx2 v[4:5], v[0:1], off offset:64
	v_cvt_pk_bf16_f32 v0, v37, v38
	v_cvt_pk_bf16_f32 v1, v6, v7
	v_mul_f32_e32 v8, v8, v32
	v_mul_f32_e32 v9, v9, v32
	v_mul_f32_e32 v10, v10, v32
	v_mul_f32_e32 v11, v11, v32
	global_store_dwordx2 v[4:5], v[0:1], off offset:80
	v_cvt_pk_bf16_f32 v0, v8, v9
	v_cvt_pk_bf16_f32 v1, v10, v11
	v_mul_f32_e32 v12, v12, v32
	v_mul_f32_e32 v13, v13, v32
	v_mul_f32_e32 v14, v14, v32
	v_mul_f32_e32 v15, v15, v32
	global_store_dwordx2 v[4:5], v[0:1], off offset:96
	v_cvt_pk_bf16_f32 v0, v12, v13
	v_cvt_pk_bf16_f32 v1, v14, v15
	global_store_dwordx2 v[4:5], v[0:1], off offset:112
